# speedup vs baseline: 1.0448x; 1.0074x over previous
.LBB0_481:
	s_cmp_gt_i32 s34, 3
	s_cselect_b64 s[0:1], -1, 0
	s_cmp_lt_i32 s35, 3
	s_cselect_b64 s[4:5], -1, 0
	s_or_b64 s[0:1], s[0:1], s[4:5]
	s_and_b64 vcc, exec, s[0:1]
	s_cbranch_vccnz .LBB0_536
	v_and_b32_e32 v1, 0x3ff, v0
	s_mov_b64 s[0:1], 0
	v_mov_b32_e32 v3, v1
	s_load_dword s3, s[92:93], 0xd8
	v_ashrrev_i32_e32 v107, 6, v3
	v_and_b32_e32 v102, 15, v3
	v_bfe_u32 v6, v3, 4, 2
	v_and_b32_e32 v10, 48, v3
	s_waitcnt lgkmcnt(0)
	s_and_b32 s0, s3, 7
	s_cmp_lg_u32 s0, 0
	s_cselect_b64 s[4:5], -1, 0
	s_cmp_lt_i32 s3, 8
	s_cselect_b64 s[6:7], -1, 0
	s_lshl_b32 s0, s2, 5
	s_and_b32 s61, s0, 0xe0
	s_movk_i32 s0, 0x4300
	v_mul_lo_u32 v2, v107, s0
	v_add_u32_e32 v5, 0, v2
	v_and_b32_e32 v2, 63, v3
	v_lshrrev_b32_e32 v3, 1, v3
	v_lshlrev_b32_e32 v4, 3, v6
	v_mov_b32_e32 v105, 0
	v_mul_u32_u24_e32 v7, 0x210, v102
	s_movk_i32 s0, 0x110
	v_and_b32_e32 v104, 24, v3
	s_or_b64 s[36:37], s[6:7], s[4:5]
	v_lshlrev_b32_e32 v106, 2, v6
	v_and_b32_e32 v6, 8, v4
	v_lshrrev_b32_e32 v200, 1, v102
	v_mul_u32_u24_e32 v200, 0x410, v200
	v_and_b32_e32 v201, 1, v102
	v_lshlrev_b32_e32 v201, 3, v201
	v_lshl_add_u32 v201, v10, 1, v201
	v_add3_u32 v137, v5, v200, v201
	v_mad_u32_u24 v7, v102, s0, v5
	v_lshlrev_b32_e32 v11, 3, v2
	v_lshlrev_b32_e32 v12, 2, v2
	v_lshl_add_u64 v[8:9], s[86:87], 0, v[104:105]
	s_mov_b64 s[4:5], 0x4c00200
	s_mov_b32 s1, 0
	s_lshr_b32 s33, s3, 3
	s_ashr_i32 s60, s2, 3
	v_lshlrev_b32_e32 v136, 6, v102
	v_mov_b32_e32 v103, v105
	v_lshl_add_u64 v[108:109], v[8:9], 0, s[4:5]
	s_mov_b32 s62, 0x2ac0000
	s_mov_b32 s63, 0x2ac4000
	v_lshlrev_b32_e32 v110, 1, v4
	s_mov_b64 s[38:39], 0x2a00000
	s_mov_b32 s64, 0x2a01000
	s_mov_b64 s[40:41], 0x2a80000
	s_mov_b32 s65, 0x2a80000
	s_mov_b32 s66, 0x2ac8000
	s_mov_b32 s67, 0x2acc000
	s_mov_b64 s[44:45], 0x4c00000
	v_lshlrev_b32_e32 v112, 1, v6
	s_mov_b64 s[46:47], 0x400
	v_lshlrev_b32_e32 v104, 2, v2
	v_add_u32_e32 v138, v7, v10
	v_lshl_add_u32 v139, v2, 4, v5
	v_add_u32_e32 v140, v5, v12
	s_mov_b32 s68, 0
	s_branch .LBB0_484

.LBB0_489:
	s_or_b64 exec, exec, s[56:57]
	v_ashrrev_i32_e32 v92, 10, v58
	s_waitcnt vmcnt(0)
	v_mul_f32_e32 v58, v63, v55
	v_fmac_f32_e32 v58, v64, v54
	v_mul_f32_e32 v82, v64, v55
	v_fma_f32 v82, v63, v54, -v82
	v_add_f32_e32 v58, v91, v58
	v_add_f32_e32 v82, v90, v82
	v_cndmask_b32_e64 v55, v55, v58, s[22:23]
	v_cndmask_b32_e64 v54, v54, v82, s[22:23]
	v_mul_f32_e32 v58, v63, v55
	v_fmac_f32_e32 v58, v64, v54
	v_mul_f32_e32 v82, v64, v55
	v_fma_f32 v82, v63, v54, -v82
	v_add_f32_e32 v58, v89, v58
	v_add_f32_e32 v82, v88, v82
	v_cndmask_b32_e64 v55, v55, v58, s[24:25]
	v_cndmask_b32_e64 v54, v54, v82, s[24:25]
	v_mul_f32_e32 v58, v63, v55
	v_fmac_f32_e32 v58, v64, v54
	v_mul_f32_e32 v82, v64, v55
	v_fma_f32 v82, v63, v54, -v82
	v_add_f32_e32 v58, v87, v58
	v_add_f32_e32 v82, v86, v82
	v_cndmask_b32_e64 v58, v55, v58, s[26:27]
	v_ashrrev_i32_e32 v93, 31, v92
	v_cndmask_b32_e64 v82, v54, v82, s[26:27]
	v_mul_f32_e32 v85, v63, v58
	v_mul_f32_e32 v54, v64, v58
	v_lshlrev_b64 v[114:115], 13, v[92:93]
	v_fmac_f32_e32 v85, v64, v82
	v_fma_f32 v90, v63, v82, -v54
	v_lshl_or_b32 v114, v57, 9, v114
	v_lshlrev_b32_e32 v54, 14, v56
	v_mov_b32_e32 v55, v105
	v_lshl_add_u64 v[54:55], v[114:115], 0, v[54:55]
	v_add_f32_e32 v57, v81, v85
	v_or_b32_e32 v54, v54, v102
	v_add_f32_e32 v56, v80, v90
	v_cndmask_b32_e64 v57, v58, v57, s[4:5]
	v_lshlrev_b64 v[94:95], 5, v[54:55]
	v_cndmask_b32_e64 v56, v82, v56, s[4:5]
	v_mul_f32_e32 v58, v63, v57
	v_lshl_add_u64 v[54:55], s[50:51], 0, v[94:95]
	v_fmac_f32_e32 v58, v64, v56
	v_mul_f32_e32 v80, v64, v57
	v_lshl_add_u64 v[54:55], v[54:55], 0, s[44:45]
	v_mov_b32_e32 v113, v105
	v_fma_f32 v80, v63, v56, -v80
	v_add_f32_e32 v58, v77, v58
	v_lshl_add_u64 v[116:117], v[54:55], 0, v[112:113]
	v_add_f32_e32 v76, v76, v80
	v_cndmask_b32_e64 v57, v57, v58, s[8:9]
	global_load_dwordx4 v[86:89], v[116:117], off
	v_cndmask_b32_e64 v56, v56, v76, s[8:9]
	v_mul_f32_e32 v58, v63, v57
	v_fmac_f32_e32 v58, v64, v56
	v_mul_f32_e32 v76, v64, v57
	v_fma_f32 v76, v63, v56, -v76
	v_add_f32_e32 v58, v73, v58
	v_add_f32_e32 v61, v61, v76
	v_cndmask_b32_e64 v57, v57, v58, s[10:11]
	v_cndmask_b32_e64 v56, v56, v61, s[10:11]
	v_mul_f32_e32 v58, v63, v57
	v_fmac_f32_e32 v58, v64, v56
	v_mul_f32_e32 v61, v64, v57
	v_fma_f32 v61, v63, v56, -v61
	v_add_f32_e32 v58, v60, v58
	v_add_f32_e32 v59, v59, v61
	v_cndmask_b32_e64 v57, v57, v58, s[12:13]
	v_cndmask_b32_e64 v56, v56, v59, s[12:13]
	v_mul_f32_e32 v58, v63, v57
	v_mul_f32_e32 v59, v64, v57
	v_fmac_f32_e32 v58, v64, v56
	v_fma_f32 v59, v63, v56, -v59
	v_add_f32_e32 v59, v83, v59
	v_add_f32_e32 v58, v84, v58
	v_cndmask_b32_e64 v73, v56, v59, s[20:21]
	v_cndmask_b32_e64 v76, v57, v58, s[20:21]
	v_lshlrev_b32_e32 v56, 1, v106
	v_mov_b32_e32 v57, v105
	v_lshl_add_u64 v[122:123], v[54:55], 0, v[56:57]
	global_load_dwordx4 v[54:57], v[116:117], off offset:512
	global_load_dwordx2 v[124:125], v[122:123], off offset:512
	global_load_dwordx2 v[126:127], v[122:123], off
	global_load_dwordx4 v[58:61], v[116:117], off offset:1024
	v_mul_f32_e32 v77, v63, v76
	v_fmac_f32_e32 v77, v64, v73
	v_mul_f32_e32 v80, v64, v76
	v_fma_f32 v80, v63, v73, -v80
	v_add_f32_e32 v72, v72, v77
	v_add_f32_e32 v71, v71, v80
	v_cndmask_b32_e32 v72, v76, v72, vcc
	v_cndmask_b32_e32 v71, v73, v71, vcc
	v_mul_f32_e32 v73, v63, v72
	v_fmac_f32_e32 v73, v64, v71
	v_mul_f32_e32 v76, v64, v72
	v_fma_f32 v76, v63, v71, -v76
	v_add_f32_e32 v68, v68, v73
	v_add_f32_e32 v67, v67, v76
	v_cndmask_b32_e64 v68, v72, v68, s[28:29]
	v_cndmask_b32_e64 v67, v71, v67, s[28:29]
	v_mul_f32_e32 v71, v63, v68
	v_fmac_f32_e32 v71, v64, v67
	v_mul_f32_e32 v72, v64, v68
	v_fma_f32 v72, v63, v67, -v72
	v_add_f32_e32 v66, v66, v71
	v_add_f32_e32 v65, v65, v72
	v_cndmask_b32_e64 v66, v68, v66, s[6:7]
	v_cndmask_b32_e64 v65, v67, v65, s[6:7]
	v_mul_f32_e32 v67, v63, v66
	v_fmac_f32_e32 v67, v64, v65
	v_mul_f32_e32 v68, v64, v66
	v_fma_f32 v68, v63, v65, -v68
	v_add_f32_e32 v67, v79, v67
	v_add_f32_e32 v68, v78, v68
	v_cndmask_b32_e64 v66, v66, v67, s[14:15]
	v_cndmask_b32_e64 v65, v65, v68, s[14:15]
	v_mul_f32_e32 v67, v63, v66
	v_fmac_f32_e32 v67, v64, v65
	v_mul_f32_e32 v68, v64, v66
	v_fma_f32 v68, v63, v65, -v68
	v_add_f32_e32 v67, v75, v67
	v_add_f32_e32 v68, v74, v68
	v_cndmask_b32_e64 v66, v66, v67, s[16:17]
	v_cndmask_b32_e64 v65, v65, v68, s[16:17]
	v_mul_f32_e32 v67, v63, v66
	s_waitcnt vmcnt(4)
	v_mfma_f32_16x16x32_bf16 v[76:79], v[18:21], v[86:89], 0
	v_fmac_f32_e32 v67, v64, v65
	v_mul_f32_e32 v64, v64, v66
	v_fma_f32 v63, v63, v65, -v64
	v_mfma_f32_16x16x32_bf16 v[72:75], v[6:9], v[86:89], 0
	v_add_f32_e32 v63, v70, v63
	v_add_f32_e32 v64, v69, v67
	v_cndmask_b32_e64 v63, v65, v63, s[18:19]
	v_mfma_f32_16x16x32_bf16 v[80:83], v[10:13], v[86:89], 0
	v_cndmask_b32_e64 v65, v66, v64, s[18:19]
	ds_write2_b64 v137, v[76:77], v[78:79] offset1:2
	s_add_u32 s4, s50, 0xac00000
	v_mfma_f32_16x16x32_bf16 v[90:93], v[14:17], v[86:89], 0
	ds_write2_b64 v137, v[72:73], v[74:75] offset0:16 offset1:18
	s_nop 2
	ds_write2_b64 v137, v[80:81], v[82:83] offset0:32 offset1:34
	s_nop 2
	ds_write2_b64 v137, v[90:91], v[92:93] offset0:48 offset1:50
	s_addc_u32 s5, s51, 0
	v_mfma_f32_16x16x32_bf16 v[66:69], v[22:25], v[86:89], 0
	v_lshlrev_b32_e32 v118, 1, v62
	v_mov_b32_e32 v119, v105
	v_lshl_add_u64 v[128:129], s[4:5], 0, v[118:119]
	v_mfma_f32_16x16x32_bf16 v[76:79], v[26:29], v[86:89], 0
	s_mov_b32 s6, 0
	v_mov_b64_e32 v[134:135], v[102:103]
	v_mfma_f32_16x16x32_bf16 v[70:73], v[30:33], v[86:89], 0
	s_nop 0
	ds_write2_b64 v137, v[66:67], v[68:69] offset0:64 offset1:66
	s_nop 2
	ds_write2_b64 v137, v[76:77], v[78:79] offset0:80 offset1:82
	s_nop 1
	ds_write2_b64 v137, v[70:71], v[72:73] offset0:96 offset1:98
	v_mfma_f32_16x16x32_bf16 v[66:69], v[34:37], v[86:89], 0
	s_nop 7
	ds_write2_b64 v137, v[66:67], v[68:69] offset0:112 offset1:114
	s_waitcnt lgkmcnt(0)
	v_or_b32_e32 v66, v114, v102
	v_mov_b32_e32 v67, v115
	v_lshlrev_b64 v[120:121], 11, v[66:67]
	v_lshl_add_u64 v[66:67], s[48:49], 0, v[94:95]
	v_lshl_add_u64 v[130:131], v[128:129], 0, v[120:121]
	v_lshl_add_u64 v[132:133], v[108:109], 0, v[66:67]
.LBB0_490:
	s_waitcnt vmcnt(3)
	v_mfma_f32_16x16x32_bf16 v[90:93], v[18:21], v[54:57], 0
	v_add_u32_e32 v111, 0x800, v139
	v_add_u32_e32 v113, 0x1000, v139
	v_add_u32_e32 v119, 0x1800, v139
	v_mfma_f32_16x16x32_bf16 v[94:97], v[6:9], v[54:57], 0
	ds_read_b128 v[82:85], v138 offset:12800
	ds_read_b128 v[78:81], v138 offset:12864
	ds_read_b128 v[74:77], v138 offset:12928
	ds_read_b128 v[70:73], v138 offset:12992
	ds_read_b128 v[98:101], v139
	ds_read_b128 v[144:147], v139 offset:1040
	ds_read_b128 v[152:155], v139 offset:2080
	ds_read_b128 v[156:159], v139 offset:3120
	v_mfma_f32_16x16x32_bf16 v[148:151], v[10:13], v[54:57], 0
	ds_read_b128 v[164:167], v139 offset:4160
	ds_read_b128 v[168:171], v139 offset:5200
	ds_read_b128 v[86:89], v139 offset:6240
	ds_read_b128 v[66:69], v139 offset:7280
	ds_write2_b64 v137, v[90:91], v[92:93] offset1:2
	v_mfma_f32_16x16x32_bf16 v[160:163], v[14:17], v[54:57], 0
	ds_write2_b64 v137, v[94:95], v[96:97] offset0:16 offset1:18
	s_nop 0
	ds_write2_b64 v137, v[148:149], v[150:151] offset0:32 offset1:34
	s_nop 4
	ds_write2_b64 v137, v[160:161], v[162:163] offset0:48 offset1:50
	s_min_u32 s0, s6, 28
	v_mfma_f32_16x16x32_bf16 v[172:175], v[22:25], v[54:57], 0
	s_lshl_b32 s0, s0, 9
	s_waitcnt lgkmcnt(11)
	v_fma_f32 v62, -v142, v65, v98
	v_fma_f32 v64, v142, v63, v99
	v_mfma_f32_16x16x32_bf16 v[90:93], v[26:29], v[54:57], 0
	s_cmp_eq_u32 s6, 0
	v_mfma_f32_16x16x32_bf16 v[94:97], v[30:33], v[54:57], 0
	s_nop 0
	ds_write2_b64 v137, v[172:173], v[174:175] offset0:64 offset1:66
	s_nop 3
	ds_write2_b64 v137, v[90:91], v[92:93] offset0:80 offset1:82
	s_nop 0
	ds_write2_b64 v137, v[94:95], v[96:97] offset0:96 offset1:98
	v_fmac_f32_e32 v62, v141, v63
	v_mfma_f32_16x16x32_bf16 v[54:57], v[34:37], v[54:57], 0
	v_fmac_f32_e32 v64, v141, v65
	v_add_u32_e32 v65, 0x2000, v140
	v_fma_f32 v63, -v142, v64, v100
	s_nop 4
	ds_write2_b64 v137, v[54:55], v[56:57] offset0:112 offset1:114
	v_lshl_add_u64 v[54:55], v[116:117], 0, s[0:1]
	global_load_dwordx4 v[54:57], v[54:55], off offset:1536
	v_fmac_f32_e32 v101, v142, v62
	s_nop 0
	v_fmac_f32_e32 v63, v141, v62
	v_fmac_f32_e32 v101, v141, v64
	v_cvt_pk_bf16_f32 v62, v62, v64
	v_cvt_pk_bf16_f32 v64, v63, v101
	ds_write2_b32 v65, v62, v64 offset0:64 offset1:132
	s_waitcnt lgkmcnt(14)
	v_fma_f32 v62, -v142, v101, v144
	v_fma_f32 v64, v142, v63, v145
	v_add_u32_e32 v65, 0x2200, v140
	v_fmac_f32_e32 v62, v141, v63
	v_fmac_f32_e32 v64, v141, v101
	s_nop 0
	v_fma_f32 v63, -v142, v64, v146
	v_fmac_f32_e32 v147, v142, v62
	s_nop 0
	v_fmac_f32_e32 v63, v141, v62
	v_fmac_f32_e32 v147, v141, v64
	v_cvt_pk_bf16_f32 v62, v62, v64
	v_cvt_pk_bf16_f32 v64, v63, v147
	ds_write2_b32 v65, v62, v64 offset0:72 offset1:140
	v_fma_f32 v62, -v142, v147, v152
	v_fma_f32 v64, v142, v63, v153
	v_add_u32_e32 v65, 0x2400, v140
	v_fmac_f32_e32 v62, v141, v63
	v_fmac_f32_e32 v64, v141, v147
	s_nop 0
	v_fma_f32 v63, -v142, v64, v154
	v_fmac_f32_e32 v155, v142, v62
	s_nop 0
	v_fmac_f32_e32 v63, v141, v62
	v_fmac_f32_e32 v155, v141, v64
	v_cvt_pk_bf16_f32 v62, v62, v64
	v_cvt_pk_bf16_f32 v64, v63, v155
	ds_write2_b32 v65, v62, v64 offset0:80 offset1:148
	s_waitcnt lgkmcnt(14)
	v_fma_f32 v62, -v142, v155, v156
	v_fma_f32 v64, v142, v63, v157
	v_add_u32_e32 v65, 0x2600, v140
	v_fmac_f32_e32 v62, v141, v63
	v_fmac_f32_e32 v64, v141, v155
	s_nop 0
	v_fma_f32 v63, -v142, v64, v158
	v_fmac_f32_e32 v159, v142, v62
	s_nop 0
	v_fmac_f32_e32 v63, v141, v62
	v_fmac_f32_e32 v159, v141, v64
	v_cvt_pk_bf16_f32 v62, v62, v64
	v_cvt_pk_bf16_f32 v64, v63, v159
	ds_write2_b32 v65, v62, v64 offset0:88 offset1:156
	v_fma_f32 v62, -v142, v159, v164
	v_fma_f32 v64, v142, v63, v165
	v_add_u32_e32 v65, 0x2800, v140
	v_fmac_f32_e32 v62, v141, v63
	v_fmac_f32_e32 v64, v141, v159
	s_nop 0
	v_fma_f32 v63, -v142, v64, v166
	v_fmac_f32_e32 v167, v142, v62
	s_nop 0
	v_fmac_f32_e32 v63, v141, v62
	v_fmac_f32_e32 v167, v141, v64
	v_cvt_pk_bf16_f32 v62, v62, v64
	v_cvt_pk_bf16_f32 v64, v63, v167
	ds_write2_b32 v65, v62, v64 offset0:96 offset1:164
	s_waitcnt lgkmcnt(14)
	v_fma_f32 v62, -v142, v167, v168
	v_fma_f32 v64, v142, v63, v169
	v_add_u32_e32 v65, 0x2a00, v140
	v_fmac_f32_e32 v62, v141, v63
	v_fmac_f32_e32 v64, v141, v167
	s_nop 0
	v_fma_f32 v63, -v142, v64, v170
	v_fmac_f32_e32 v171, v142, v62
	s_nop 0
	v_fmac_f32_e32 v63, v141, v62
	v_fmac_f32_e32 v171, v141, v64
	v_cvt_pk_bf16_f32 v62, v62, v64
	v_cvt_pk_bf16_f32 v64, v63, v171
	ds_write2_b32 v65, v62, v64 offset0:104 offset1:172
	v_fma_f32 v62, -v142, v171, v86
	v_fma_f32 v64, v142, v63, v87
	v_add_u32_e32 v65, 0x2c00, v140
	v_fmac_f32_e32 v62, v141, v63
	v_fmac_f32_e32 v64, v141, v171
	s_nop 0
	v_fmac_f32_e32 v89, v142, v62
	v_fma_f32 v63, -v142, v64, v88
	s_nop 0
	v_fmac_f32_e32 v89, v141, v64
	v_fmac_f32_e32 v63, v141, v62
	v_cvt_pk_bf16_f32 v62, v62, v64
	s_waitcnt lgkmcnt(14)
	v_fma_f32 v86, -v142, v89, v66
	v_cvt_pk_bf16_f32 v64, v63, v89
	ds_write2_b32 v65, v62, v64 offset0:112 offset1:180
	v_fma_f32 v67, v142, v63, v67
	v_fmac_f32_e32 v86, v141, v63
	v_mfma_f32_16x16x32_bf16 v[62:65], v[50:53], v[82:85], 0
	v_mfma_f32_16x16x32_bf16 v[62:65], v[46:49], v[78:81], v[62:65]
	v_fmac_f32_e32 v67, v141, v89
	v_fmac_f32_e32 v69, v142, v86
	v_mfma_f32_16x16x32_bf16 v[62:65], v[42:45], v[74:77], v[62:65]
	v_fma_f32 v66, -v142, v67, v68
	v_mfma_f32_16x16x32_bf16 v[62:65], v[38:41], v[70:73], v[62:65]
	v_fmac_f32_e32 v66, v141, v86
	v_fmac_f32_e32 v69, v141, v67
	v_cvt_pk_bf16_f32 v67, v86, v67
	v_cvt_pk_bf16_f32 v68, v66, v69
	v_add_u32_e32 v74, 0x2e00, v140
	ds_write2_b32 v74, v67, v68 offset0:120 offset1:188
	s_cbranch_scc1 .LBB0_492
	s_waitcnt vmcnt(3)
	v_lshlrev_b32_e32 v70, 16, v124
	v_and_b32_e32 v71, 0xffff0000, v124
	v_pk_fma_f32 v[62:63], v[2:3], v[70:71], v[62:63]
	v_lshlrev_b32_e32 v72, 16, v125
	v_mul_f32_e32 v67, 0x3d372713, v62
	v_mul_f32_e32 v67, v62, v67
	v_mul_f32_e32 v68, 0x3d372713, v63
	v_fma_f32 v67, v62, v67, v62
	v_mul_f32_e32 v68, v63, v68
	v_mul_f32_e32 v67, 0x3f4c422a, v67
	v_fma_f32 v68, v63, v68, v63
	v_add_f32_e32 v67, v67, v67
	v_mul_f32_e32 v68, 0x3f4c422a, v68
	v_mul_f32_e32 v67, 0x3fb8aa3b, v67
	v_add_f32_e32 v68, v68, v68
	v_exp_f32_e32 v67, v67
	v_mul_f32_e32 v68, 0x3fb8aa3b, v68
	v_exp_f32_e32 v68, v68
	v_and_b32_e32 v73, 0xffff0000, v125
	v_add_f32_e32 v67, 1.0, v67
	v_rcp_f32_e32 v70, v67
	v_add_f32_e32 v67, 1.0, v68
	v_pk_fma_f32 v[64:65], v[4:5], v[72:73], v[64:65]
	v_rcp_f32_e32 v71, v67
	v_mul_f32_e32 v67, 0x3d372713, v64
	v_mul_f32_e32 v67, v64, v67
	v_mul_f32_e32 v68, 0x3d372713, v65
	v_fma_f32 v67, v64, v67, v64
	v_mul_f32_e32 v68, v65, v68
	v_mul_f32_e32 v67, 0x3f4c422a, v67
	v_fma_f32 v68, v65, v68, v65
	v_add_f32_e32 v67, v67, v67
	v_mul_f32_e32 v68, 0x3f4c422a, v68
	v_mul_f32_e32 v67, 0x3fb8aa3b, v67
	v_add_f32_e32 v68, v68, v68
	v_exp_f32_e32 v67, v67
	v_mul_f32_e32 v68, 0x3fb8aa3b, v68
	v_exp_f32_e32 v68, v68
	v_pk_fma_f32 v[70:71], v[70:71], 2.0, 1.0 op_sel_hi:[1,0,0] neg_lo:[1,0,0] neg_hi:[1,0,0]
	v_add_f32_e32 v67, 1.0, v67
	v_rcp_f32_e32 v72, v67
	v_add_f32_e32 v67, 1.0, v68
	v_rcp_f32_e32 v73, v67
	v_pk_mul_f32 v[62:63], v[62:63], 0.5 op_sel_hi:[1,0]
	v_pk_add_f32 v[70:71], v[70:71], 1.0 op_sel_hi:[1,0]
	s_add_i32 s0, s6, -1
	v_pk_mul_f32 v[62:63], v[62:63], v[70:71]
	v_pk_fma_f32 v[70:71], v[72:73], 2.0, 1.0 op_sel_hi:[1,0,0] neg_lo:[1,0,0] neg_hi:[1,0,0]
	v_pk_mul_f32 v[64:65], v[64:65], 0.5 op_sel_hi:[1,0]
	v_pk_add_f32 v[70:71], v[70:71], 1.0 op_sel_hi:[1,0]
	s_lshl_b64 s[8:9], s[0:1], 15
	v_pk_mul_f32 v[64:65], v[64:65], v[70:71]
	v_cvt_pk_bf16_f32 v62, v62, v63
	v_cvt_pk_bf16_f32 v63, v64, v65
	v_lshl_add_u64 v[64:65], v[130:131], 0, s[8:9]
	global_store_dwordx2 v[64:65], v[62:63], off
	global_load_dwordx2 v[124:125], v[132:133], off
.LBB0_492:
	s_waitcnt lgkmcnt(0)
	ds_read_b128 v[98:101], v138 offset:8448
	ds_read_b128 v[94:97], v138 offset:8512
	ds_read_b128 v[90:93], v138 offset:8576
	ds_read_b128 v[86:89], v138 offset:8640
	ds_read_b128 v[156:159], v139
	ds_read_b128 v[160:163], v139 offset:1040
	ds_read_b128 v[164:167], v139 offset:2080
	s_waitcnt vmcnt(1)
	v_mfma_f32_16x16x32_bf16 v[144:147], v[18:21], v[58:61], 0
	ds_read_b128 v[82:85], v139 offset:3120
	ds_read_b128 v[78:81], v139 offset:4160
	ds_read_b128 v[74:77], v139 offset:5200
	s_waitcnt lgkmcnt(5)
	v_fma_f32 v67, -v142, v69, v156
	v_fma_f32 v68, v142, v66, v157
	v_mfma_f32_16x16x32_bf16 v[148:151], v[6:9], v[58:61], 0
	ds_read_b128 v[70:73], v139 offset:6240
	ds_read_b128 v[62:65], v139 offset:7280
	v_mfma_f32_16x16x32_bf16 v[152:155], v[10:13], v[58:61], 0
	v_fmac_f32_e32 v67, v141, v66
	v_fmac_f32_e32 v68, v141, v69
	ds_write2_b64 v137, v[144:145], v[146:147] offset1:2
	v_mfma_f32_16x16x32_bf16 v[168:171], v[14:17], v[58:61], 0
	s_nop 0
	ds_write2_b64 v137, v[148:149], v[150:151] offset0:16 offset1:18
	s_nop 1
	ds_write2_b64 v137, v[152:153], v[154:155] offset0:32 offset1:34
	s_nop 2
	ds_write2_b64 v137, v[168:169], v[170:171] offset0:48 offset1:50
	v_mfma_f32_16x16x32_bf16 v[172:175], v[22:25], v[58:61], 0
	v_fmac_f32_e32 v159, v142, v67
	v_fma_f32 v66, -v142, v68, v158
	v_mfma_f32_16x16x32_bf16 v[144:147], v[26:29], v[58:61], 0
	v_add_u32_e32 v69, 0x3000, v140
	v_mfma_f32_16x16x32_bf16 v[148:151], v[30:33], v[58:61], 0
	v_fmac_f32_e32 v66, v141, v67
	v_fmac_f32_e32 v159, v141, v68
	v_mfma_f32_16x16x32_bf16 v[58:61], v[34:37], v[58:61], 0
	v_cvt_pk_bf16_f32 v67, v67, v68
	v_cvt_pk_bf16_f32 v68, v66, v159
	ds_write2_b64 v137, v[172:173], v[174:175] offset0:64 offset1:66
	ds_write2_b64 v137, v[144:145], v[146:147] offset0:80 offset1:82
	s_nop 0
	ds_write2_b64 v137, v[148:149], v[150:151] offset0:96 offset1:98
	s_nop 1
	ds_write2_b64 v137, v[58:59], v[60:61] offset0:112 offset1:114
	ds_write2_b32 v69, v67, v68 offset0:128 offset1:196
	s_waitcnt lgkmcnt(14)
	v_fma_f32 v67, -v142, v159, v160
	v_fma_f32 v68, v142, v66, v161
	v_add_u32_e32 v69, 0x3400, v140
	v_fmac_f32_e32 v67, v141, v66
	v_fmac_f32_e32 v68, v141, v159
	s_add_i32 s7, s6, 1
	v_fma_f32 v66, -v142, v68, v162
	v_fmac_f32_e32 v163, v142, v67
	s_min_u32 s0, s7, 28
	v_fmac_f32_e32 v66, v141, v67
	v_fmac_f32_e32 v163, v141, v68
	v_cvt_pk_bf16_f32 v67, v67, v68
	v_cvt_pk_bf16_f32 v68, v66, v163
	ds_write2_b32 v69, v67, v68 offset0:8 offset1:76
	v_fma_f32 v67, -v142, v163, v164
	v_fma_f32 v68, v142, v66, v165
	s_lshl_b32 s0, s0, 9
	v_fmac_f32_e32 v67, v141, v66
	v_fmac_f32_e32 v68, v141, v163
	v_lshl_add_u64 v[58:59], v[116:117], 0, s[0:1]
	v_fmac_f32_e32 v167, v142, v67
	v_fma_f32 v66, -v142, v68, v166
	s_min_u32 s0, s7, 30
	v_fmac_f32_e32 v167, v141, v68
	v_fmac_f32_e32 v66, v141, v67
	v_cvt_pk_bf16_f32 v67, v67, v68
	s_waitcnt lgkmcnt(14)
	v_fma_f32 v82, -v142, v167, v82
	v_cvt_pk_bf16_f32 v68, v66, v167
	ds_write2_b32 v69, v67, v68 offset0:144 offset1:212
	v_fma_f32 v83, v142, v66, v83
	v_fmac_f32_e32 v82, v141, v66
	v_mfma_f32_16x16x32_bf16 v[66:69], v[50:53], v[98:101], 0
	s_lshl_b32 s0, s0, 9
	v_mfma_f32_16x16x32_bf16 v[66:69], v[46:49], v[94:97], v[66:69]
	v_fmac_f32_e32 v83, v141, v167
	v_fmac_f32_e32 v85, v142, v82
	v_mfma_f32_16x16x32_bf16 v[66:69], v[42:45], v[90:93], v[66:69]
	v_fma_f32 v84, -v142, v83, v84
	v_mfma_f32_16x16x32_bf16 v[66:69], v[38:41], v[86:89], v[66:69]
	v_fmac_f32_e32 v84, v141, v82
	v_fmac_f32_e32 v85, v141, v83
	v_cvt_pk_bf16_f32 v82, v82, v83
	v_cvt_pk_bf16_f32 v83, v84, v85
	v_add_u32_e32 v94, 0x3800, v140
	ds_write2_b32 v94, v82, v83 offset0:24 offset1:92
	v_lshlrev_b32_e32 v82, 16, v126
	v_and_b32_e32 v83, 0xffff0000, v126
	v_pk_fma_f32 v[66:67], v[2:3], v[82:83], v[66:67]
	v_lshlrev_b32_e32 v86, 16, v127
	v_mul_f32_e32 v82, 0x3d372713, v66
	v_mul_f32_e32 v83, 0x3d372713, v67
	v_and_b32_e32 v87, 0xffff0000, v127
	v_mul_f32_e32 v82, v66, v82
	v_mul_f32_e32 v83, v67, v83
	v_pk_fma_f32 v[68:69], v[4:5], v[86:87], v[68:69]
	v_fma_f32 v82, v66, v82, v66
	v_fma_f32 v83, v67, v83, v67
	v_mul_f32_e32 v86, 0x3d372713, v68
	v_mul_f32_e32 v87, 0x3d372713, v69
	v_mul_f32_e32 v82, 0x3f4c422a, v82
	v_mul_f32_e32 v83, 0x3f4c422a, v83
	v_mul_f32_e32 v86, v68, v86
	v_mul_f32_e32 v87, v69, v87
	v_add_f32_e32 v82, v82, v82
	v_add_f32_e32 v83, v83, v83
	v_fma_f32 v86, v68, v86, v68
	v_fma_f32 v87, v69, v87, v69
	v_mul_f32_e32 v82, 0x3fb8aa3b, v82
	v_mul_f32_e32 v83, 0x3fb8aa3b, v83
	v_mul_f32_e32 v86, 0x3f4c422a, v86
	v_mul_f32_e32 v87, 0x3f4c422a, v87
	v_exp_f32_e32 v82, v82
	v_exp_f32_e32 v83, v83
	v_add_f32_e32 v86, v86, v86
	v_add_f32_e32 v87, v87, v87
	v_mul_f32_e32 v86, 0x3fb8aa3b, v86
	v_mul_f32_e32 v87, 0x3fb8aa3b, v87
	v_exp_f32_e32 v86, v86
	v_exp_f32_e32 v87, v87
	v_add_f32_e32 v82, 1.0, v82
	v_add_f32_e32 v83, 1.0, v83
	v_rcp_f32_e32 v82, v82
	v_rcp_f32_e32 v83, v83
	v_add_f32_e32 v86, 1.0, v86
	v_add_f32_e32 v87, 1.0, v87
	v_rcp_f32_e32 v86, v86
	v_rcp_f32_e32 v87, v87
	v_pk_fma_f32 v[82:83], v[82:83], 2.0, 1.0 op_sel_hi:[1,0,0] neg_lo:[1,0,0] neg_hi:[1,0,0]
	v_pk_mul_f32 v[66:67], v[66:67], 0.5 op_sel_hi:[1,0]
	v_pk_add_f32 v[82:83], v[82:83], 1.0 op_sel_hi:[1,0]
	v_pk_mul_f32 v[68:69], v[68:69], 0.5 op_sel_hi:[1,0]
	v_pk_mul_f32 v[66:67], v[66:67], v[82:83]
	v_pk_fma_f32 v[82:83], v[86:87], 2.0, 1.0 op_sel_hi:[1,0,0] neg_lo:[1,0,0] neg_hi:[1,0,0]
	s_waitcnt lgkmcnt(14)
	v_fma_f32 v95, -v142, v85, v78
	v_pk_add_f32 v[82:83], v[82:83], 1.0 op_sel_hi:[1,0]
	v_fma_f32 v90, v142, v84, v79
	v_or_b32_e32 v79, v115, v135
	v_or_b32_e32 v78, v114, v134
	v_pk_mul_f32 v[68:69], v[68:69], v[82:83]
	v_cvt_pk_bf16_f32 v66, v66, v67
	v_cvt_pk_bf16_f32 v67, v68, v69
	v_lshlrev_b64 v[68:69], 11, v[78:79]
	v_lshl_add_u64 v[68:69], v[128:129], 0, v[68:69]
	global_load_dwordx4 v[58:61], v[58:59], off offset:1536
	global_store_dwordx2 v[68:69], v[66:67], off
	v_lshl_add_u64 v[66:67], v[122:123], 0, s[0:1]
	global_load_dwordx2 v[126:127], v[66:67], off offset:512
	v_fmac_f32_e32 v95, v141, v84
	v_fmac_f32_e32 v90, v141, v85
	v_add_u32_e32 v69, 0x3c00, v140
	v_fma_f32 v66, -v142, v90, v80
	v_fmac_f32_e32 v81, v142, v95
	v_cvt_pk_bf16_f32 v67, v95, v90
	v_fmac_f32_e32 v66, v141, v95
	v_fmac_f32_e32 v81, v141, v90
	s_add_i32 s0, s6, 2
	v_cvt_pk_bf16_f32 v68, v66, v81
	ds_write2_b32 v94, v67, v68 offset0:160 offset1:228
	v_fma_f32 v67, -v142, v81, v74
	v_fma_f32 v68, v142, v66, v75
	v_lshl_add_u64 v[132:133], v[132:133], 0, s[46:47]
	v_fmac_f32_e32 v67, v141, v66
	v_fmac_f32_e32 v68, v141, v81
	s_cmp_lt_u32 s6, 30
	v_fma_f32 v66, -v142, v68, v76
	v_fmac_f32_e32 v77, v142, v67
	v_lshl_add_u64 v[134:135], v[134:135], 0, 32
	v_fmac_f32_e32 v66, v141, v67
	v_fmac_f32_e32 v77, v141, v68
	v_cvt_pk_bf16_f32 v67, v67, v68
	v_cvt_pk_bf16_f32 v68, v66, v77
	ds_write2_b32 v69, v67, v68 offset0:40 offset1:108
	s_waitcnt lgkmcnt(14)
	v_fma_f32 v67, -v142, v77, v70
	v_fma_f32 v68, v142, v66, v71
	s_nop 0
	v_fmac_f32_e32 v67, v141, v66
	v_fmac_f32_e32 v68, v141, v77
	s_nop 0
	v_fma_f32 v66, -v142, v68, v72
	v_fmac_f32_e32 v73, v142, v67
	s_nop 0
	v_fmac_f32_e32 v66, v141, v67
	v_fmac_f32_e32 v73, v141, v68
	v_cvt_pk_bf16_f32 v67, v67, v68
	v_cvt_pk_bf16_f32 v68, v66, v73
	ds_write2_b32 v69, v67, v68 offset0:176 offset1:244
	v_fma_f32 v62, -v142, v73, v62
	v_fma_f32 v67, v142, v66, v63
	s_nop 0
	v_fmac_f32_e32 v62, v141, v66
	v_fmac_f32_e32 v67, v141, v73
	v_add_u32_e32 v66, 0x4000, v140
	v_fma_f32 v63, -v142, v67, v64
	v_fmac_f32_e32 v65, v142, v62
	s_nop 0
	v_fmac_f32_e32 v63, v141, v62
	v_fmac_f32_e32 v65, v141, v67
	v_cvt_pk_bf16_f32 v62, v62, v67
	v_cvt_pk_bf16_f32 v64, v63, v65
	ds_write2_b32 v66, v62, v64 offset0:56 offset1:124
	s_waitcnt lgkmcnt(0)
	s_cbranch_scc0 .LBB0_483
	s_mov_b32 s6, s0
	s_branch .LBB0_490

.LBB0_1001:
	s_cmp_gt_i32 s34, 9
	s_cselect_b64 s[0:1], -1, 0
	s_cmp_lt_i32 s35, 9
	s_cselect_b64 s[4:5], -1, 0
	s_or_b64 s[0:1], s[0:1], s[4:5]
	s_and_b64 vcc, exec, s[0:1]
	s_cbranch_vccnz .LBB0_1066
	s_mov_b64 s[0:1], 0
	s_load_dword s3, s[92:93], 0xd8
	v_mbcnt_lo_u32_b32 v2, -1, 0
	s_mov_b32 s1, 0
	v_and_b32_e32 v1, 0x3ff, v0
	s_waitcnt lgkmcnt(0)
	v_mov_b32_e32 v3, 0
	s_and_b32 s0, s3, 7
	s_cmp_lg_u32 s0, 0
	s_cselect_b64 s[4:5], -1, 0
	s_cmp_lt_i32 s3, 8
	s_cselect_b64 s[6:7], -1, 0
	s_lshl_b32 s0, s2, 8
	s_lshr_b32 s33, s3, 3
	s_or_b64 s[12:13], s[6:7], s[4:5]
	s_ashr_i32 s38, s2, 3
	s_and_b32 s39, s0, 0x700
	s_mov_b64 s[14:15], 0x4c00000
	s_mov_b32 s40, 0x4c00000
	s_movk_i32 s41, 0x70
	s_mov_b64 s[16:17], 0x2c00000
	s_mov_b64 s[18:19], 0x8c00000
	s_mov_b32 s44, 0x42f00000
	s_mov_b64 s[20:21], 0xac00000
	s_mov_b32 s45, 0xac00000
	s_mov_b64 s[22:23], 0x6c00000
	s_mov_b32 s46, 0x6c00000
	v_mov_b32_e32 v42, 0xff61b1e6
	v_mbcnt_hi_u32_b32 v43, -1, v2
	v_xor_b32_e32 v162, 16, v43
	v_xor_b32_e32 v163, 32, v43
	v_xor_b32_e32 v164, 48, v43
	v_lshlrev_b32_e32 v162, 2, v162
	v_lshlrev_b32_e32 v163, 2, v163
	v_lshlrev_b32_e32 v164, 2, v164
	s_mov_b32 s47, 0
	s_mov_b32 s55, 0
	s_branch .LBB0_1004

.LBB0_1017:
	s_or_b64 exec, exec, s[36:37]
	v_mul_f32_e32 v71, v97, v86
	v_mul_f32_e32 v74, v95, v71
	v_mul_f32_e32 v80, v93, v74
	v_mul_f32_e32 v88, v90, v80
	v_mul_f32_e32 v85, v85, v88
	v_mul_f32_e32 v90, v82, v85
	v_mul_f32_e32 v91, v79, v90
	v_mul_f32_e32 v76, v76, v91
	v_mul_f32_e32 v72, v72, v76
	v_mul_f32_e32 v69, v69, v72
	v_mul_f32_e32 v67, v67, v69
	v_mul_f32_e32 v65, v65, v67
	v_mul_f32_e32 v62, v62, v65
	v_mul_f32_e32 v60, v60, v62
	v_mul_f32_e32 v79, v59, v60
	s_nop 0
	ds_bpermute_b32 v83, v162, v79
	ds_bpermute_b32 v78, v163, v79
	ds_bpermute_b32 v82, v164, v79
	s_waitcnt lgkmcnt(2)
	v_cndmask_b32_e64 v59, 1.0, v83, s[10:11]
	s_waitcnt lgkmcnt(1)
	v_mul_f32_e32 v92, v59, v78
	v_cndmask_b32_e64 v59, v59, v92, s[4:5]
	s_waitcnt lgkmcnt(0)
	v_mul_f32_e32 v92, v59, v82
	v_cndmask_b32_e64 v59, v59, v92, s[6:7]
	v_mul_f32_e32 v59, v55, v59
	v_mul_f32_e32 v60, v59, v60
	v_mul_f32_e32 v56, v56, v60
	v_mul_f32_e32 v60, v59, v62
	v_mul_f32_e32 v57, v57, v60
	v_mul_f32_e32 v60, v59, v65
	v_mul_f32_e32 v58, v58, v60
	v_mul_f32_e32 v60, v59, v67
	v_mul_f32_e32 v65, v61, v60
	v_mul_f32_e32 v60, v59, v69
	v_mul_f32_e32 v67, v63, v60
	v_mul_f32_e32 v60, v59, v72
	v_mul_f32_e32 v64, v64, v60
	v_mul_f32_e32 v60, v76, v59
	v_mul_f32_e32 v69, v66, v60
	v_mul_f32_e32 v60, v91, v59
	v_mul_f32_e32 v68, v68, v60
	v_mul_f32_e32 v60, v90, v59
	v_mul_f32_e32 v70, v70, v60
	v_mul_f32_e32 v60, v85, v59
	v_mul_f32_e32 v72, v73, v60
	v_mul_f32_e32 v60, v88, v59
	v_mul_f32_e32 v73, v75, v60
	v_mul_f32_e32 v60, v80, v59
	v_mul_f32_e32 v75, v77, v60
	v_mul_f32_e32 v60, v74, v59
	v_mul_f32_e32 v76, v81, v60
	v_mul_f32_e32 v60, v71, v59
	v_mul_f32_e32 v71, v84, v60
	v_mul_f32_e32 v60, v86, v59
	v_add_u32_e32 v81, v2, v51
	v_mul_f32_e32 v77, v87, v60
	ds_read_b128 v[60:63], v81 offset:8192
	v_mul_f32_e32 v80, v89, v59
	v_cvt_pk_bf16_f32 v59, v69, v68
	v_cvt_pk_bf16_f32 v68, v70, v72
	v_cvt_pk_bf16_f32 v69, v73, v75
	ds_read_b128 v[72:75], v81 offset:10240
	v_cvt_pk_bf16_f32 v56, v56, v57
	v_cvt_pk_bf16_f32 v57, v58, v65
	v_cvt_pk_bf16_f32 v58, v67, v64
	v_add_u32_e32 v2, v2, v52
	ds_read_b128 v[64:67], v2 offset:8192
	s_waitcnt lgkmcnt(2)
	v_mfma_f32_16x16x32_bf16 v[8:11], v[60:63], v[56:59], v[8:11]
	ds_read_b128 v[60:63], v2 offset:10240
	v_cvt_pk_bf16_f32 v70, v76, v71
	v_cvt_pk_bf16_f32 v71, v77, v80
	s_waitcnt lgkmcnt(2)
	v_mfma_f32_16x16x32_bf16 v[12:15], v[72:75], v[56:59], v[12:15]
	s_waitcnt lgkmcnt(1)
	v_mfma_f32_16x16x32_bf16 v[8:11], v[64:67], v[68:71], v[8:11]
	s_waitcnt lgkmcnt(0)
	v_mfma_f32_16x16x32_bf16 v[12:15], v[60:63], v[68:71], v[12:15]
	ds_read_b128 v[60:63], v81 offset:12288
	ds_read_b128 v[64:67], v81 offset:14336
	s_waitcnt lgkmcnt(1)
	v_mfma_f32_16x16x32_bf16 v[16:19], v[60:63], v[56:59], v[16:19]
	ds_read_b128 v[60:63], v2 offset:12288
	ds_read_b128 v[72:75], v2 offset:14336
	s_waitcnt lgkmcnt(2)
	v_mfma_f32_16x16x32_bf16 v[4:7], v[64:67], v[56:59], v[4:7]
	v_mul_f32_e64 v56, v78, v82
	v_mul_f32_e64 v57, v79, v83
	v_mul_f32_e32 v2, v56, v57
	v_mul_f32_e32 v55, v55, v2
	s_waitcnt lgkmcnt(1)
	v_mfma_f32_16x16x32_bf16 v[16:19], v[60:63], v[68:71], v[16:19]
	v_cmp_eq_f32_e32 vcc, 0, v55
	s_cmp_eq_u64 vcc, exec
	s_cselect_b64 s[36:37], -1, 0
	s_waitcnt lgkmcnt(0)
	v_mfma_f32_16x16x32_bf16 v[4:7], v[72:75], v[68:71], v[4:7]
	v_cndmask_b32_e64 v56, 0, 1, s[36:37]
